# plus: redundant vmcnt(0) before the q/k-norm gain multiplies (iterations 2-8) and before the in-projection K-loop removed
# baseline (speedup 1.0000x reference)
; #define PG8_STAGE(bufoff, gbase, voff) do { _Pragma("unroll") for (int _i = 0; _i < 2; ++_i) \
;         __builtin_amdgcn_global_load_lds((const unsigned*)((const char*)(gbase) + (voff)[_i]), (LAS unsigned*)(lds + (bufoff) + ldsw + _i * 8192), 16, 0, 0); } while (0)
; #define PG8_LDA(dst, b, h) do { _Pragma("unroll") for (int m = 0; m < 4; ++m) _Pragma("unroll") for (int k = 0; k < 2; ++k) dst[m][k] = *(const LAS bf16x8*)(lds + PG8_SA(b, h) + aoff + m * 2048 + k * 1024); } while (0)
; #define PG8_LDB(dst, b, h) do { _Pragma("unroll") for (int n = 0; n < 2; ++n) _Pragma("unroll") for (int k = 0; k < 2; ++k) dst[n][k] = *(const LAS bf16x8*)(lds + PG8_SB(b, h) + boff + n * 2048 + k * 1024); } while (0)
; #define PG8_WAIT_V(n) asm volatile("s_waitcnt vmcnt(" #n ")" ::: "memory")
; #define PG8_WAIT_L(n) asm volatile("s_waitcnt lgkmcnt(" #n ")" ::: "memory")
; #define PG8_BAR __builtin_amdgcn_s_barrier()
; #define PG8_SCHED __builtin_amdgcn_sched_barrier(0)
; template <class Epi, class Sched, bool ALIGN_EPI = false, bool SP2 = false>
; __device__ __forceinline__ void gemm_phase(LAS unsigned char* lds, const Gemm g, const Sched& S, const Epi& E) {
;     ...
;         const char* nA = has_next ? (const char*)g.A + (size_t)nxt.pm * g.a_tstep : cA; const char* nB = has_next ? (const char*)g.Bt + (size_t)nxt.pn * tstep : cB;
;         for (int t = 0; t < nt; t += 2) {
;             const bool last = (t == nt - 2);
;             const char* a1 = cA + (size_t)(t + 1) * kstep;
;             const char* a2 = last ? nA : cA + (size_t)(t + 2) * kstep; const char* b2 = last ? nB : cB + (size_t)(t + 2) * kstep;
;             const char* a3 = a2 + kstep; const char* b3 = b2 + kstep;
;             if (last && has_next) S.a_ready(nxt);
;             if constexpr (SP2) {
;             PG8_LDB(B0, 0, 0); PG8_LDB(B1, 0, 1); PG8_SCHED; PG8_LDA(At, 0, 0); PG8_STAGE(PG8_SA(1, 1), a1 + hstep, voffA);
;             PG8_WAIT_V(8); PG8_WAIT_L(0); PG8_BAR; PG8_MMA(0, 0, At, B0); PG8_MMA(0, 1, At, B1); PG8_BAR; PG8_SCHED;
;     ...
;         for (int a = 0; a < 2; ++a)
; #pragma unroll
;             for (int b = 0; b < 2; ++b)
; #pragma unroll
;                 for (int m = 0; m < 4; ++m)
; #pragma unroll
;                     for (int n = 0; n < 2; ++n) acc[a][b][m][n] = (f32x4){0.f, 0.f, 0.f, 0.f};
;         cur = nxt; cA = nA; cB = nB; ++ui;
.LBB0_333:
	v_readlane_b32 s48, v252, 31
	v_readlane_b32 s49, v252, 32
	s_ashr_i32 s35, s34, 31
	s_mov_b32 s55, -2
	v_mov_b64_e32 v[0:1], s[48:49]
	v_cmp_lt_i64_e32 vcc, s[46:47], v[0:1]
	s_lshl_b64 s[46:47], s[34:35], 19
	s_add_u32 s46, s78, s46
	s_addc_u32 s47, s79, s47
	s_and_b64 s[48:49], vcc, exec
	s_cselect_b32 s35, s47, s43
	s_cselect_b32 s41, s46, s42
	s_ashr_i32 s31, s30, 31
	s_lshl_b64 s[48:49], s[30:31], 19
	s_add_u32 s48, s66, s48
	s_addc_u32 s49, s67, s49
	s_and_b64 s[50:51], vcc, exec
	s_cselect_b32 s31, s49, s45
	s_cselect_b32 s52, s48, s44
	s_add_u32 s42, s42, 0x40080
	s_addc_u32 s43, s43, 0
	s_add_u32 s53, s44, 0x100
	v_mov_b64_e32 v[0:1], 0
	s_addc_u32 s54, s45, 0
	v_mov_b64_e32 v[2:3], 0
	v_mov_b64_e32 v[4:5], 0
	v_mov_b64_e32 v[6:7], 0
	v_mov_b64_e32 v[16:17], 0
	v_mov_b64_e32 v[18:19], 0
	v_mov_b64_e32 v[20:21], 0
	v_mov_b64_e32 v[22:23], 0
	v_mov_b64_e32 v[32:33], 0
	v_mov_b64_e32 v[34:35], 0
	v_mov_b64_e32 v[36:37], 0
	v_mov_b64_e32 v[38:39], 0
	v_mov_b64_e32 v[48:49], 0
	v_mov_b64_e32 v[50:51], 0
	v_mov_b64_e32 v[52:53], 0
	v_mov_b64_e32 v[54:55], 0
	v_mov_b64_e32 v[8:9], 0
	v_mov_b64_e32 v[10:11], 0
	v_mov_b64_e32 v[12:13], 0
	v_mov_b64_e32 v[14:15], 0
	v_mov_b64_e32 v[24:25], 0
	v_mov_b64_e32 v[26:27], 0
	v_mov_b64_e32 v[28:29], 0
	v_mov_b64_e32 v[30:31], 0
	v_mov_b64_e32 v[40:41], 0
	v_mov_b64_e32 v[42:43], 0
	v_mov_b64_e32 v[44:45], 0
	v_mov_b64_e32 v[46:47], 0
	v_mov_b64_e32 v[56:57], 0
	v_mov_b64_e32 v[58:59], 0
	v_mov_b64_e32 v[60:61], 0
	v_mov_b64_e32 v[62:63], 0
	v_mov_b64_e32 v[76:77], 0
	v_mov_b64_e32 v[78:79], 0
	v_mov_b64_e32 v[84:85], 0
	v_mov_b64_e32 v[86:87], 0
	v_mov_b64_e32 v[96:97], 0
	v_mov_b64_e32 v[98:99], 0
	v_mov_b64_e32 v[100:101], 0
	v_mov_b64_e32 v[102:103], 0
	v_mov_b64_e32 v[112:113], 0
	v_mov_b64_e32 v[114:115], 0
	v_mov_b64_e32 v[116:117], 0
	v_mov_b64_e32 v[118:119], 0
	v_mov_b64_e32 v[130:131], 0
	v_mov_b64_e32 v[132:133], 0
	v_mov_b64_e32 v[134:135], 0
	v_mov_b64_e32 v[136:137], 0
	v_mov_b64_e32 v[88:89], 0
	v_mov_b64_e32 v[90:91], 0
	v_mov_b64_e32 v[92:93], 0
	v_mov_b64_e32 v[94:95], 0
	v_mov_b64_e32 v[104:105], 0
	v_mov_b64_e32 v[106:107], 0
	v_mov_b64_e32 v[108:109], 0
	v_mov_b64_e32 v[110:111], 0
	v_mov_b64_e32 v[120:121], 0
	v_mov_b64_e32 v[122:123], 0
	v_mov_b64_e32 v[124:125], 0
	v_mov_b64_e32 v[126:127], 0
	v_mov_b64_e32 v[138:139], 0
	v_mov_b64_e32 v[140:141], 0
	v_mov_b64_e32 v[142:143], 0
	v_mov_b64_e32 v[144:145], 0
.LBB0_334:
	v_or_b32_e32 v64, 0x10000, v163
	v_add_u32_e32 v68, 0x10400, v163
	v_add_u32_e32 v72, 0x10800, v163
	v_add_u32_e32 v80, 0x10c00, v163
	v_or_b32_e32 v156, 0x14000, v163
	v_add_u32_e32 v164, 0x14400, v163
	v_add_u32_e32 v168, 0x14800, v163
	ds_read_b128 v[64:67], v64
	ds_read_b128 v[68:71], v68
	ds_read_b128 v[72:75], v72
	ds_read_b128 v[80:83], v80
	ds_read_b128 v[156:159], v156
	ds_read_b128 v[164:167], v164
	v_add_u32_e32 v169, 0x14c00, v163
	ds_read_b128 v[172:175], v168
	ds_read_b128 v[176:179], v169
	s_add_u32 s44, s42, 0xfffc0080
	s_addc_u32 s45, s43, -1
	s_cmp_eq_u32 s55, 12
	s_cselect_b32 s51, s35, s45
	s_cselect_b32 s50, s41, s44
	s_cselect_b32 s45, s31, s54
	s_cselect_b32 s44, s52, s53
	v_lshl_add_u64 v[168:169], s[42:43], 0, v[152:153]
	s_add_i32 m0, s68, 0xc000
	ds_read_b128 v[180:183], v162
	ds_read_b128 v[184:187], v162 offset:1024
	ds_read_b128 v[188:191], v162 offset:2048
	ds_read_b128 v[192:195], v162 offset:3072
	ds_read_b128 v[208:211], v162 offset:4096
	ds_read_b128 v[212:215], v162 offset:5120
	ds_read_b128 v[216:219], v162 offset:6144
	ds_read_b128 v[220:223], v162 offset:7168
	global_load_lds_dwordx4 v[168:169], off
	v_lshl_add_u64 v[168:169], s[42:43], 0, v[154:155]
	s_add_i32 m0, s68, 0xe000
	s_nop 0
	global_load_lds_dwordx4 v[168:169], off
	s_waitcnt vmcnt(8)
	s_waitcnt lgkmcnt(0)
	s_barrier
	s_setprio 1
	s_waitcnt lgkmcnt(0)
	v_mfma_f32_16x16x32_bf16 v[142:145], v[64:67], v[180:183], v[142:145]
	v_mfma_f32_16x16x32_bf16 v[138:141], v[72:75], v[180:183], v[138:141]
	v_mfma_f32_16x16x32_bf16 v[124:127], v[64:67], v[188:191], v[124:127]
	v_mfma_f32_16x16x32_bf16 v[120:123], v[72:75], v[188:191], v[120:123]
	v_mfma_f32_16x16x32_bf16 v[108:111], v[64:67], v[208:211], v[108:111]
	v_mfma_f32_16x16x32_bf16 v[104:107], v[72:75], v[208:211], v[104:107]
	v_mfma_f32_16x16x32_bf16 v[92:95], v[64:67], v[216:219], v[92:95]
	v_mfma_f32_16x16x32_bf16 v[88:91], v[72:75], v[216:219], v[88:91]
	v_mfma_f32_16x16x32_bf16 v[142:145], v[68:71], v[184:187], v[142:145]
	v_mfma_f32_16x16x32_bf16 v[138:141], v[80:83], v[184:187], v[138:141]
	v_mfma_f32_16x16x32_bf16 v[124:127], v[68:71], v[192:195], v[124:127]
	v_mfma_f32_16x16x32_bf16 v[120:123], v[80:83], v[192:195], v[120:123]
	v_mfma_f32_16x16x32_bf16 v[108:111], v[68:71], v[212:215], v[108:111]
	v_mfma_f32_16x16x32_bf16 v[104:107], v[80:83], v[212:215], v[104:107]
	v_mfma_f32_16x16x32_bf16 v[92:95], v[68:71], v[220:223], v[92:95]
	v_mfma_f32_16x16x32_bf16 v[88:91], v[80:83], v[220:223], v[88:91]
	s_setprio 0
	s_setprio 1
	v_mfma_f32_16x16x32_bf16 v[134:137], v[156:159], v[180:183], v[134:137]
	v_mfma_f32_16x16x32_bf16 v[130:133], v[172:175], v[180:183], v[130:133]
	v_mfma_f32_16x16x32_bf16 v[116:119], v[156:159], v[188:191], v[116:119]
	v_mfma_f32_16x16x32_bf16 v[112:115], v[172:175], v[188:191], v[112:115]
	v_mfma_f32_16x16x32_bf16 v[100:103], v[156:159], v[208:211], v[100:103]
	v_mfma_f32_16x16x32_bf16 v[96:99], v[172:175], v[208:211], v[96:99]
	v_mfma_f32_16x16x32_bf16 v[84:87], v[156:159], v[216:219], v[84:87]
	v_mfma_f32_16x16x32_bf16 v[76:79], v[172:175], v[216:219], v[76:79]
	v_mfma_f32_16x16x32_bf16 v[134:137], v[164:167], v[184:187], v[134:137]
	v_mfma_f32_16x16x32_bf16 v[130:133], v[176:179], v[184:187], v[130:133]
	v_mfma_f32_16x16x32_bf16 v[116:119], v[164:167], v[192:195], v[116:119]
	v_mfma_f32_16x16x32_bf16 v[112:115], v[176:179], v[192:195], v[112:115]
	v_mfma_f32_16x16x32_bf16 v[100:103], v[164:167], v[212:215], v[100:103]
	v_mfma_f32_16x16x32_bf16 v[96:99], v[176:179], v[212:215], v[96:99]
	v_mfma_f32_16x16x32_bf16 v[84:87], v[164:167], v[220:223], v[84:87]
	v_mfma_f32_16x16x32_bf16 v[76:79], v[176:179], v[220:223], v[76:79]
	s_setprio 0
	s_barrier
; #define PG8_STAGE(bufoff, gbase, voff) do { _Pragma("unroll") for (int _i = 0; _i < 2; ++_i) \
;         __builtin_amdgcn_global_load_lds((const unsigned*)((const char*)(gbase) + (voff)[_i]), (LAS unsigned*)(lds + (bufoff) + ldsw + _i * 8192), 16, 0, 0); } while (0)
; #define PG8_LDA(dst, b, h) do { _Pragma("unroll") for (int m = 0; m < 4; ++m) _Pragma("unroll") for (int k = 0; k < 2; ++k) dst[m][k] = *(const LAS bf16x8*)(lds + PG8_SA(b, h) + aoff + m * 2048 + k * 1024); } while (0)
; #define PG8_LDB(dst, b, h) do { _Pragma("unroll") for (int n = 0; n < 2; ++n) _Pragma("unroll") for (int k = 0; k < 2; ++k) dst[n][k] = *(const LAS bf16x8*)(lds + PG8_SB(b, h) + boff + n * 2048 + k * 1024); } while (0)
; #define PG8_MMA(ai, bj, At, Bt) do { __builtin_amdgcn_s_setprio(1); _Pragma("unroll") for (int m = 0; m < 4; ++m) _Pragma("unroll") for (int n = 0; n < 2; ++n) _Pragma("unroll") for (int k = 0; k < 2; ++k) \
;         acc[ai][bj][m][n] = __builtin_amdgcn_mfma_f32_16x16x32_bf16(Bt[n][k], At[m][k], acc[ai][bj][m][n], 0, 0, 0); __builtin_amdgcn_s_setprio(0); } while (0)
; #define PG8_WAIT_V(n) asm volatile("s_waitcnt vmcnt(" #n ")" ::: "memory")
; #define PG8_WAIT_L(n) asm volatile("s_waitcnt lgkmcnt(" #n ")" ::: "memory")
; #define PG8_BAR __builtin_amdgcn_s_barrier()
; #define PG8_SCHED __builtin_amdgcn_sched_barrier(0)
; template <class Epi, class Sched, bool ALIGN_EPI = false, bool SP2 = false>
; __device__ __forceinline__ void gemm_phase(LAS unsigned char* lds, const Gemm g, const Sched& S, const Epi& E) {
;     ...
;             PG8_LDA(At, 0, 1); PG8_STAGE(PG8_SB(0, 0), b2, voffB); PG8_STAGE(PG8_SB(0, 1), b2 + hstep, voffB); PG8_STAGE(PG8_SA(0, 0), a2, voffA);
;             PG8_WAIT_V(8); PG8_WAIT_L(0); PG8_BAR; PG8_MMA(1, 0, At, B0); PG8_MMA(1, 1, At, B1); PG8_BAR; PG8_SCHED;
;             PG8_LDB(B0, 1, 0); PG8_LDB(B1, 1, 1); PG8_SCHED; PG8_LDA(At, 1, 0); PG8_STAGE(PG8_SA(0, 1), a2 + hstep, voffA);
;             PG8_WAIT_V(8); PG8_WAIT_L(0); PG8_BAR; PG8_MMA(0, 0, At, B0); PG8_MMA(0, 1, At, B1); PG8_BAR; PG8_SCHED;
	s_mov_b32 m0, s69
	v_lshl_add_u64 v[168:169], s[44:45], 0, v[128:129]
	s_add_u32 s58, s44, 0x40000
	ds_read_b128 v[180:183], v162 offset:16384
	ds_read_b128 v[184:187], v162 offset:17408
	ds_read_b128 v[188:191], v162 offset:18432
	ds_read_b128 v[192:195], v162 offset:19456
	ds_read_b128 v[208:211], v162 offset:20480
	ds_read_b128 v[212:215], v162 offset:21504
	ds_read_b128 v[216:219], v162 offset:22528
	ds_read_b128 v[220:223], v162 offset:23552
	global_load_lds_dwordx4 v[168:169], off
	v_lshl_add_u64 v[196:197], s[44:45], 0, v[150:151]
	s_mov_b32 m0, s72
	s_addc_u32 s59, s45, 0
	global_load_lds_dwordx4 v[196:197], off
	v_lshl_add_u64 v[224:225], s[58:59], 0, v[128:129]
	s_mov_b32 m0, s73
	v_lshl_add_u64 v[226:227], s[50:51], 0, v[148:149]
	global_load_lds_dwordx4 v[224:225], off
	v_lshl_add_u64 v[224:225], s[58:59], 0, v[150:151]
	s_mov_b32 m0, s65
	s_nop 0
	global_load_lds_dwordx4 v[224:225], off
	v_lshl_add_u64 v[224:225], s[50:51], 0, v[146:147]
	s_mov_b32 m0, s68
	s_nop 0
	global_load_lds_dwordx4 v[224:225], off
	s_mov_b32 m0, s22
	s_nop 0
	global_load_lds_dwordx4 v[226:227], off
	s_waitcnt vmcnt(8)
	s_waitcnt lgkmcnt(0)
	s_barrier
	s_setprio 1
	s_waitcnt lgkmcnt(0)
	v_mfma_f32_16x16x32_bf16 v[60:63], v[64:67], v[180:183], v[60:63]
	v_mfma_f32_16x16x32_bf16 v[56:59], v[72:75], v[180:183], v[56:59]
	v_mfma_f32_16x16x32_bf16 v[44:47], v[64:67], v[188:191], v[44:47]
	v_mfma_f32_16x16x32_bf16 v[40:43], v[72:75], v[188:191], v[40:43]
	v_mfma_f32_16x16x32_bf16 v[28:31], v[64:67], v[208:211], v[28:31]
	v_mfma_f32_16x16x32_bf16 v[24:27], v[72:75], v[208:211], v[24:27]
	v_mfma_f32_16x16x32_bf16 v[12:15], v[64:67], v[216:219], v[12:15]
	v_mfma_f32_16x16x32_bf16 v[8:11], v[72:75], v[216:219], v[8:11]
	v_mfma_f32_16x16x32_bf16 v[60:63], v[68:71], v[184:187], v[60:63]
	v_mfma_f32_16x16x32_bf16 v[56:59], v[80:83], v[184:187], v[56:59]
	v_mfma_f32_16x16x32_bf16 v[44:47], v[68:71], v[192:195], v[44:47]
	v_mfma_f32_16x16x32_bf16 v[40:43], v[80:83], v[192:195], v[40:43]
	v_mfma_f32_16x16x32_bf16 v[28:31], v[68:71], v[212:215], v[28:31]
	v_mfma_f32_16x16x32_bf16 v[24:27], v[80:83], v[212:215], v[24:27]
	v_mfma_f32_16x16x32_bf16 v[12:15], v[68:71], v[220:223], v[12:15]
	v_mfma_f32_16x16x32_bf16 v[8:11], v[80:83], v[220:223], v[8:11]
	s_setprio 0
	s_setprio 1
	v_mfma_f32_16x16x32_bf16 v[52:55], v[156:159], v[180:183], v[52:55]
	v_mfma_f32_16x16x32_bf16 v[48:51], v[172:175], v[180:183], v[48:51]
	v_mfma_f32_16x16x32_bf16 v[36:39], v[156:159], v[188:191], v[36:39]
	v_mfma_f32_16x16x32_bf16 v[32:35], v[172:175], v[188:191], v[32:35]
	v_mfma_f32_16x16x32_bf16 v[20:23], v[156:159], v[208:211], v[20:23]
	v_mfma_f32_16x16x32_bf16 v[16:19], v[172:175], v[208:211], v[16:19]
	v_mfma_f32_16x16x32_bf16 v[4:7], v[156:159], v[216:219], v[4:7]
	v_mfma_f32_16x16x32_bf16 v[0:3], v[172:175], v[216:219], v[0:3]
	v_mfma_f32_16x16x32_bf16 v[52:55], v[164:167], v[184:187], v[52:55]
	v_mfma_f32_16x16x32_bf16 v[48:51], v[176:179], v[184:187], v[48:51]
	v_mfma_f32_16x16x32_bf16 v[36:39], v[164:167], v[192:195], v[36:39]
	v_mfma_f32_16x16x32_bf16 v[32:35], v[176:179], v[192:195], v[32:35]
	v_mfma_f32_16x16x32_bf16 v[20:23], v[164:167], v[212:215], v[20:23]
	v_mfma_f32_16x16x32_bf16 v[16:19], v[176:179], v[212:215], v[16:19]
	v_mfma_f32_16x16x32_bf16 v[4:7], v[164:167], v[220:223], v[4:7]
	v_mfma_f32_16x16x32_bf16 v[0:3], v[176:179], v[220:223], v[0:3]
	s_setprio 0
	s_barrier
	v_or_b32_e32 v64, 0x18000, v163
	v_add_u32_e32 v68, 0x18400, v163
	v_add_u32_e32 v72, 0x18800, v163
	v_add_u32_e32 v80, 0x18c00, v163
	v_or_b32_e32 v156, 0x1c000, v163
	v_add_u32_e32 v164, 0x1c400, v163
	v_add_u32_e32 v172, 0x1c800, v163
	v_add_u32_e32 v176, 0x1cc00, v163
	ds_read_b128 v[64:67], v64
	ds_read_b128 v[68:71], v68
	ds_read_b128 v[72:75], v72
	ds_read_b128 v[80:83], v80
	ds_read_b128 v[156:159], v156
	ds_read_b128 v[164:167], v164
	ds_read_b128 v[172:175], v172
	ds_read_b128 v[176:179], v176
	s_add_u32 s50, s50, 0x40000
	s_addc_u32 s51, s51, 0
	s_mov_b32 m0, s23
	v_lshl_add_u64 v[228:229], s[50:51], 0, v[146:147]
	ds_read_b128 v[180:183], v162 offset:32768
	ds_read_b128 v[184:187], v162 offset:33792
	ds_read_b128 v[188:191], v162 offset:34816
	ds_read_b128 v[192:195], v162 offset:35840
	ds_read_b128 v[208:211], v162 offset:36864
	ds_read_b128 v[212:215], v162 offset:37888
	ds_read_b128 v[216:219], v162 offset:38912
	ds_read_b128 v[220:223], v162 offset:39936
	global_load_lds_dwordx4 v[228:229], off
	v_lshl_add_u64 v[228:229], s[50:51], 0, v[148:149]
	s_mov_b32 m0, s0
	s_nop 0
	global_load_lds_dwordx4 v[228:229], off
	s_waitcnt vmcnt(8)
	s_waitcnt lgkmcnt(0)
	s_barrier
; #define PG8_STAGE(bufoff, gbase, voff) do { _Pragma("unroll") for (int _i = 0; _i < 2; ++_i) \
;         __builtin_amdgcn_global_load_lds((const unsigned*)((const char*)(gbase) + (voff)[_i]), (LAS unsigned*)(lds + (bufoff) + ldsw + _i * 8192), 16, 0, 0); } while (0)
; #define PG8_LDA(dst, b, h) do { _Pragma("unroll") for (int m = 0; m < 4; ++m) _Pragma("unroll") for (int k = 0; k < 2; ++k) dst[m][k] = *(const LAS bf16x8*)(lds + PG8_SA(b, h) + aoff + m * 2048 + k * 1024); } while (0)
; #define PG8_WAIT_V(n) asm volatile("s_waitcnt vmcnt(" #n ")" ::: "memory")
; #define PG8_WAIT_L(n) asm volatile("s_waitcnt lgkmcnt(" #n ")" ::: "memory")
; #define PG8_BAR __builtin_amdgcn_s_barrier()
; #define PG8_SCHED __builtin_amdgcn_sched_barrier(0)
; template <class Epi, class Sched, bool ALIGN_EPI = false, bool SP2 = false>
; __device__ __forceinline__ void gemm_phase(LAS unsigned char* lds, const Gemm g, const Sched& S, const Epi& E) {
;     ...
;             PG8_WAIT_V(8); PG8_WAIT_L(0); PG8_BAR; PG8_MMA(0, 0, At, B0); PG8_MMA(0, 1, At, B1); PG8_BAR; PG8_SCHED;
;             PG8_LDA(At, 1, 1); PG8_STAGE(PG8_SB(1, 0), b3, voffB); PG8_STAGE(PG8_SB(1, 1), b3 + hstep, voffB); PG8_STAGE(PG8_SA(1, 0), a3, voffA);
;             PG8_WAIT_V(8); PG8_WAIT_L(0); PG8_BAR; PG8_MMA(1, 0, At, B0); PG8_MMA(1, 1, At, B1); PG8_BAR; PG8_SCHED;
;     DI void operator()(const f32x4 (&acc)[2][2][4][2], const Unit& u, int wr, int wc, int fr_in, int fq_in) const {
;     ...
;         const int cb = u.pn * 256 + wc * 64;
;         bf16_t* dst; int ld, dcol; const float* gain = nullptr; bool rope = false; float scale = 1.f;
;         if (even) {
;             if (cb < 512) { dst = P; ld = 512; dcol = cb; }
;             else if (cb < 1024) { dst = P + (size_t)NR * 512; ld = 512; dcol = cb - 512; rope = true; scale = QSCALE; }
;             else if (cb < 1152) { dst = P + (size_t)NR * 1024; ld = 128; dcol = cb - 1024; rope = true; }
;             else { dst = P + (size_t)NR * 1152; ld = 128; dcol = cb - 1152; }
;         } else {
;             if (cb < 1024) { dst = P; ld = 1024; dcol = cb; gain = qg; rope = true; scale = QSCALE; }
;             else if (cb < 1280) { dst = P + (size_t)NR * 1024; ld = 256; dcol = cb - 1024; gain = kg; rope = true; }
;             else { dst = P + (size_t)NR * 1280; ld = 256; dcol = cb - 1280; }
	s_setprio 1
	s_waitcnt lgkmcnt(0)
	v_mfma_f32_16x16x32_bf16 v[142:145], v[64:67], v[180:183], v[142:145]
	v_mfma_f32_16x16x32_bf16 v[138:141], v[72:75], v[180:183], v[138:141]
	v_mfma_f32_16x16x32_bf16 v[124:127], v[64:67], v[188:191], v[124:127]
	v_mfma_f32_16x16x32_bf16 v[120:123], v[72:75], v[188:191], v[120:123]
	v_mfma_f32_16x16x32_bf16 v[108:111], v[64:67], v[208:211], v[108:111]
	v_mfma_f32_16x16x32_bf16 v[104:107], v[72:75], v[208:211], v[104:107]
	v_mfma_f32_16x16x32_bf16 v[92:95], v[64:67], v[216:219], v[92:95]
	v_mfma_f32_16x16x32_bf16 v[88:91], v[72:75], v[216:219], v[88:91]
	v_mfma_f32_16x16x32_bf16 v[142:145], v[68:71], v[184:187], v[142:145]
	v_mfma_f32_16x16x32_bf16 v[138:141], v[80:83], v[184:187], v[138:141]
	v_mfma_f32_16x16x32_bf16 v[124:127], v[68:71], v[192:195], v[124:127]
	v_mfma_f32_16x16x32_bf16 v[120:123], v[80:83], v[192:195], v[120:123]
	v_mfma_f32_16x16x32_bf16 v[108:111], v[68:71], v[212:215], v[108:111]
	v_mfma_f32_16x16x32_bf16 v[104:107], v[80:83], v[212:215], v[104:107]
	v_mfma_f32_16x16x32_bf16 v[92:95], v[68:71], v[220:223], v[92:95]
	v_mfma_f32_16x16x32_bf16 v[88:91], v[80:83], v[220:223], v[88:91]
	s_setprio 0
	s_setprio 1
	v_mfma_f32_16x16x32_bf16 v[134:137], v[156:159], v[180:183], v[134:137]
	v_mfma_f32_16x16x32_bf16 v[130:133], v[172:175], v[180:183], v[130:133]
	v_mfma_f32_16x16x32_bf16 v[116:119], v[156:159], v[188:191], v[116:119]
	v_mfma_f32_16x16x32_bf16 v[112:115], v[172:175], v[188:191], v[112:115]
	v_mfma_f32_16x16x32_bf16 v[100:103], v[156:159], v[208:211], v[100:103]
	v_mfma_f32_16x16x32_bf16 v[96:99], v[172:175], v[208:211], v[96:99]
	v_mfma_f32_16x16x32_bf16 v[84:87], v[156:159], v[216:219], v[84:87]
	v_mfma_f32_16x16x32_bf16 v[76:79], v[172:175], v[216:219], v[76:79]
	v_mfma_f32_16x16x32_bf16 v[134:137], v[164:167], v[184:187], v[134:137]
	v_mfma_f32_16x16x32_bf16 v[130:133], v[176:179], v[184:187], v[130:133]
	v_mfma_f32_16x16x32_bf16 v[116:119], v[164:167], v[192:195], v[116:119]
	v_mfma_f32_16x16x32_bf16 v[112:115], v[176:179], v[192:195], v[112:115]
	v_mfma_f32_16x16x32_bf16 v[100:103], v[164:167], v[212:215], v[100:103]
	v_mfma_f32_16x16x32_bf16 v[96:99], v[176:179], v[212:215], v[96:99]
	v_mfma_f32_16x16x32_bf16 v[84:87], v[164:167], v[220:223], v[84:87]
	v_mfma_f32_16x16x32_bf16 v[76:79], v[176:179], v[220:223], v[76:79]
	s_setprio 0
	s_barrier
	s_mov_b32 m0, s70
	v_lshl_add_u64 v[168:169], v[168:169], 0, s[24:25]
	s_add_u32 s44, s44, 0x40080
	ds_read_b128 v[180:183], v162 offset:49152
	ds_read_b128 v[184:187], v162 offset:50176
	ds_read_b128 v[188:191], v162 offset:51200
	ds_read_b128 v[192:195], v162 offset:52224
	ds_read_b128 v[208:211], v162 offset:53248
	ds_read_b128 v[212:215], v162 offset:54272
	ds_read_b128 v[216:219], v162 offset:55296
	ds_read_b128 v[220:223], v162 offset:56320
	global_load_lds_dwordx4 v[168:169], off
	v_lshl_add_u64 v[168:169], v[196:197], 0, s[24:25]
	s_mov_b32 m0, s71
	s_addc_u32 s45, s45, 0
	global_load_lds_dwordx4 v[168:169], off
	v_lshl_add_u64 v[168:169], s[44:45], 0, v[128:129]
	s_mov_b32 m0, s2
	s_nop 0
	global_load_lds_dwordx4 v[168:169], off
	v_lshl_add_u64 v[168:169], s[44:45], 0, v[150:151]
	s_mov_b32 m0, s26
	s_nop 0
	global_load_lds_dwordx4 v[168:169], off
	v_lshl_add_u64 v[168:169], v[224:225], 0, s[24:25]
	s_mov_b32 m0, s97
	s_nop 0
	global_load_lds_dwordx4 v[168:169], off
	v_lshl_add_u64 v[168:169], v[226:227], 0, s[24:25]
	s_mov_b32 m0, s99
	s_nop 0
	global_load_lds_dwordx4 v[168:169], off
	s_waitcnt vmcnt(8)
	s_waitcnt lgkmcnt(0)
	s_barrier
	s_setprio 1
	s_waitcnt lgkmcnt(0)
	v_mfma_f32_16x16x32_bf16 v[60:63], v[64:67], v[180:183], v[60:63]
	v_mfma_f32_16x16x32_bf16 v[56:59], v[72:75], v[180:183], v[56:59]
	v_mfma_f32_16x16x32_bf16 v[44:47], v[64:67], v[188:191], v[44:47]
	v_mfma_f32_16x16x32_bf16 v[40:43], v[72:75], v[188:191], v[40:43]
	v_mfma_f32_16x16x32_bf16 v[28:31], v[64:67], v[208:211], v[28:31]
	v_mfma_f32_16x16x32_bf16 v[24:27], v[72:75], v[208:211], v[24:27]
	v_mfma_f32_16x16x32_bf16 v[12:15], v[64:67], v[216:219], v[12:15]
	v_mfma_f32_16x16x32_bf16 v[8:11], v[72:75], v[216:219], v[8:11]
	v_mfma_f32_16x16x32_bf16 v[60:63], v[68:71], v[184:187], v[60:63]
	v_mfma_f32_16x16x32_bf16 v[56:59], v[80:83], v[184:187], v[56:59]
	v_mfma_f32_16x16x32_bf16 v[44:47], v[68:71], v[192:195], v[44:47]
	v_mfma_f32_16x16x32_bf16 v[40:43], v[80:83], v[192:195], v[40:43]
	v_mfma_f32_16x16x32_bf16 v[28:31], v[68:71], v[212:215], v[28:31]
	v_mfma_f32_16x16x32_bf16 v[24:27], v[80:83], v[212:215], v[24:27]
	v_mfma_f32_16x16x32_bf16 v[12:15], v[68:71], v[220:223], v[12:15]
	v_mfma_f32_16x16x32_bf16 v[8:11], v[80:83], v[220:223], v[8:11]
	s_setprio 0
	s_setprio 1
	v_mfma_f32_16x16x32_bf16 v[52:55], v[156:159], v[180:183], v[52:55]
	v_mfma_f32_16x16x32_bf16 v[48:51], v[172:175], v[180:183], v[48:51]
	v_mfma_f32_16x16x32_bf16 v[36:39], v[156:159], v[188:191], v[36:39]
	v_mfma_f32_16x16x32_bf16 v[32:35], v[172:175], v[188:191], v[32:35]
	v_mfma_f32_16x16x32_bf16 v[20:23], v[156:159], v[208:211], v[20:23]
	v_mfma_f32_16x16x32_bf16 v[16:19], v[172:175], v[208:211], v[16:19]
	v_mfma_f32_16x16x32_bf16 v[4:7], v[156:159], v[216:219], v[4:7]
	v_mfma_f32_16x16x32_bf16 v[0:3], v[172:175], v[216:219], v[0:3]
	v_mfma_f32_16x16x32_bf16 v[52:55], v[164:167], v[184:187], v[52:55]
	v_mfma_f32_16x16x32_bf16 v[48:51], v[176:179], v[184:187], v[48:51]
	v_mfma_f32_16x16x32_bf16 v[36:39], v[164:167], v[192:195], v[36:39]
	v_mfma_f32_16x16x32_bf16 v[32:35], v[176:179], v[192:195], v[32:35]
	v_mfma_f32_16x16x32_bf16 v[20:23], v[164:167], v[212:215], v[20:23]
	v_mfma_f32_16x16x32_bf16 v[16:19], v[176:179], v[212:215], v[16:19]
	v_mfma_f32_16x16x32_bf16 v[4:7], v[164:167], v[220:223], v[4:7]
	v_mfma_f32_16x16x32_bf16 v[0:3], v[176:179], v[220:223], v[0:3]
	s_setprio 0
	s_barrier
	s_add_i32 s55, s55, 2
	s_add_u32 s42, s42, 0x100
	s_addc_u32 s43, s43, 0
	s_add_u32 s53, s53, 0x100
	s_addc_u32 s54, s54, 0
	s_cmp_gt_u32 s55, 13
	s_cbranch_scc0 .LBB0_334
	s_lshl_b32 s35, s40, 8
	v_readlane_b32 s40, v254, 20
	v_readlane_b32 s41, v254, 21
	v_mov_b32_e32 v168, v161
	v_mov_b32_e32 v167, v160
	s_or_b32 s31, s35, s27
	s_mov_b64 s[42:43], -1
	s_and_b64 vcc, exec, s[40:41]
	s_cbranch_vccz .LBB0_342
	s_cmpk_lt_i32 s31, 0x400
	s_cbranch_scc1 .LBB0_341
	s_cmpk_gt_u32 s35, 0x4ff
	s_mov_b64 s[40:41], -1
	s_cbranch_scc0 .LBB0_339
	s_add_i32 s60, s31, 0xfffffb00
	s_mov_b64 s[40:41], 0

; DI float shx(float v, int k, int lane) { return __builtin_bit_cast(float, __builtin_amdgcn_ds_bpermute((lane ^ k) << 2, __builtin_bit_cast(int, v))); }
; DI unsigned pack2(float lo, float hi) { f32x2 v = {lo, hi}; bf16x2_t b = __builtin_convertvector(v, bf16x2_t); return __builtin_bit_cast(unsigned, b); }
;     DI void operator()(const f32x4 (&acc)[2][2][4][2], const Unit& u, int wr, int wc, int fr_in, int fq_in) const {
;     ...
;                 if (gain) {
;                     float ss = 0.f;
; #pragma unroll
;                     for (int bj = 0; bj < 2; ++bj)
; #pragma unroll
;                         for (int n = 0; n < 2; ++n)
; #pragma unroll
;                             for (int e = 0; e < 4; ++e) ss += x[bj][n][e] * x[bj][n][e];
;                     ss += shx(ss, 16, fq * 16 + fr); ss += shx(ss, 32, fq * 16 + fr);
;                     const float rinv = rsqrtf(ss * (1.0f / 64.0f) + EPS);
; #pragma unroll
;                     for (int bj = 0; bj < 2; ++bj)
; #pragma unroll
;                         for (int n = 0; n < 2; ++n) x[bj][n] = x[bj][n] * rinv * gn[bj][n];
;                 }
;                 if (rope && row < NLAT) {
;                     const int t = row & (T - 1), pr = t >> 6, pc = t & 63;
;                     const int idx = (fq < 2) ? (pr * 16 + 8 * fq) : (pc * 16 + 8 * fq - 16);
; #pragma unroll
;                     for (int n = 0; n < 2; ++n) {
;                         const f32x4 cs = *(const f32x4*)(ROPE_COS + idx + 4 * n), sn = *(const f32x4*)(ROPE_SIN + idx + 4 * n);
;                         const f32x4 x1 = x[0][n], x2 = x[1][n];
;                         x[0][n] = x1 * cs - x2 * sn;
;                         x[1][n] = x2 * cs + x1 * sn;
;                     }
;                 }
;                 bf16_t* rp = dst + (size_t)row * ld + dcol + 8 * fq;
; #pragma unroll
;                 for (int bj = 0; bj < 2; ++bj) {
;                     const f32x4 v0 = x[bj][0] * scale, v1 = x[bj][1] * scale;
;                     u32x4 w; w.x = pack2(v0[0], v0[1]); w.y = pack2(v0[2], v0[3]); w.z = pack2(v1[0], v1[1]); w.w = pack2(v1[2], v1[3]);
;                     *(u32x4*)(rp + 32 * bj) = w;
;                 }
.LBB0_373:
	s_or_b64 exec, exec, s[56:57]
	s_ashr_i32 s61, s60, 31
	s_lshl_b64 s[56:57], s[60:61], 1
	s_add_u32 s56, s58, s56
	s_addc_u32 s57, s59, s57
	v_lshl_add_u64 v[156:157], v[158:159], 1, s[56:57]
	v_ashrrev_i32_e32 v159, 31, v169
	v_mul_lo_u32 v174, s53, v169
	v_mul_lo_u32 v159, s52, v159
	v_mad_u64_u32 v[172:173], s[56:57], s52, v169, 0
	v_add3_u32 v173, v173, v159, v174
	v_pk_mul_f32 v[144:145], s[50:51], v[144:145] op_sel_hi:[0,1]
	v_pk_mul_f32 v[142:143], s[50:51], v[142:143] op_sel_hi:[0,1]
	v_pk_mul_f32 v[174:175], s[50:51], v[140:141] op_sel_hi:[0,1]
	v_pk_mul_f32 v[140:141], s[50:51], v[138:139] op_sel_hi:[0,1]
	v_lshl_add_u64 v[172:173], v[172:173], 1, v[156:157]
	v_cvt_pk_bf16_f32 v138, v142, v143
	v_cvt_pk_bf16_f32 v139, v144, v145
	v_cvt_pk_bf16_f32 v140, v140, v141
	v_cvt_pk_bf16_f32 v141, v174, v175
	global_store_dwordx4 v[172:173], v[138:141], off
	v_pk_mul_f32 v[136:137], s[50:51], v[136:137] op_sel_hi:[0,1]
	v_pk_mul_f32 v[134:135], s[50:51], v[134:135] op_sel_hi:[0,1]
	v_pk_mul_f32 v[138:139], s[50:51], v[132:133] op_sel_hi:[0,1]
	v_pk_mul_f32 v[132:133], s[50:51], v[130:131] op_sel_hi:[0,1]
	v_cvt_pk_bf16_f32 v130, v134, v135
	v_cvt_pk_bf16_f32 v131, v136, v137
	v_cvt_pk_bf16_f32 v132, v132, v133
	v_cvt_pk_bf16_f32 v133, v138, v139
	s_and_b64 vcc, exec, s[40:41]
	global_store_dwordx4 v[172:173], v[130:133], off offset:64
	s_cbranch_vccnz .LBB0_375
	v_mul_f32_e32 v134, v125, v125
	v_fmac_f32_e32 v134, v124, v124
	v_fmac_f32_e32 v134, v126, v126
	v_fmac_f32_e32 v134, v127, v127
	v_fmac_f32_e32 v134, v120, v120
	v_fmac_f32_e32 v134, v121, v121
	v_fmac_f32_e32 v134, v122, v122
	v_fmac_f32_e32 v134, v123, v123
	v_pk_mul_f32 v[132:133], v[116:117], v[116:117]
	v_pk_mul_f32 v[130:131], v[118:119], v[118:119]
	v_add_f32_e32 v132, v134, v132
	v_add_f32_e32 v132, v133, v132
	v_add_f32_e32 v130, v130, v132
	v_add_f32_e32 v134, v131, v130
	v_pk_mul_f32 v[132:133], v[112:113], v[112:113]
	v_pk_mul_f32 v[130:131], v[114:115], v[114:115]
	v_add_f32_e32 v132, v132, v134
	v_add_f32_e32 v132, v133, v132
	v_add_f32_e32 v130, v130, v132
	v_add_f32_e32 v130, v131, v130
	ds_bpermute_b32 v131, v164, v130
	s_waitcnt lgkmcnt(0)
	v_add_f32_e32 v130, v130, v131
	ds_bpermute_b32 v131, v165, v130
	s_waitcnt lgkmcnt(0)
	v_add_f32_e32 v130, v130, v131
	v_fmamk_f32 v130, v130, 0x3c800000, v170
	v_mul_f32_e32 v131, 0x4b800000, v130
	v_cmp_gt_f32_e32 vcc, s75, v130
	s_nop 1
	v_cndmask_b32_e32 v130, v130, v131, vcc
	v_rsq_f32_e32 v130, v130
	s_nop 0
	v_mul_f32_e32 v131, 0x45800000, v130
	v_cndmask_b32_e32 v130, v130, v131, vcc
	v_pk_mul_f32 v[124:125], v[124:125], v[130:131] op_sel_hi:[1,0]
	v_pk_mul_f32 v[126:127], v[126:127], v[130:131] op_sel_hi:[1,0]
	v_pk_mul_f32 v[120:121], v[120:121], v[130:131] op_sel_hi:[1,0]
	v_pk_mul_f32 v[122:123], v[122:123], v[130:131] op_sel_hi:[1,0]
	v_pk_mul_f32 v[116:117], v[116:117], v[130:131] op_sel_hi:[1,0]
	v_pk_mul_f32 v[118:119], v[118:119], v[130:131] op_sel_hi:[1,0]
	v_pk_mul_f32 v[112:113], v[112:113], v[130:131] op_sel_hi:[1,0]
	v_pk_mul_f32 v[114:115], v[114:115], v[130:131] op_sel_hi:[1,0]
	v_pk_mul_f32 v[126:127], v[70:71], v[126:127]
	v_pk_mul_f32 v[124:125], v[68:69], v[124:125]
	v_pk_mul_f32 v[122:123], v[66:67], v[122:123]
	v_pk_mul_f32 v[120:121], v[64:65], v[120:121]
	v_pk_mul_f32 v[118:119], v[82:83], v[118:119]
	v_pk_mul_f32 v[116:117], v[80:81], v[116:117]
	v_pk_mul_f32 v[114:115], v[74:75], v[114:115]
	v_pk_mul_f32 v[112:113], v[72:73], v[112:113]

; DI float shx(float v, int k, int lane) { return __builtin_bit_cast(float, __builtin_amdgcn_ds_bpermute((lane ^ k) << 2, __builtin_bit_cast(int, v))); }
; DI unsigned pack2(float lo, float hi) { f32x2 v = {lo, hi}; bf16x2_t b = __builtin_convertvector(v, bf16x2_t); return __builtin_bit_cast(unsigned, b); }
;     DI void operator()(const f32x4 (&acc)[2][2][4][2], const Unit& u, int wr, int wc, int fr_in, int fq_in) const {
;     ...
;                 if (gain) {
;                     float ss = 0.f;
; #pragma unroll
;                     for (int bj = 0; bj < 2; ++bj)
; #pragma unroll
;                         for (int n = 0; n < 2; ++n)
; #pragma unroll
;                             for (int e = 0; e < 4; ++e) ss += x[bj][n][e] * x[bj][n][e];
;                     ss += shx(ss, 16, fq * 16 + fr); ss += shx(ss, 32, fq * 16 + fr);
;                     const float rinv = rsqrtf(ss * (1.0f / 64.0f) + EPS);
; #pragma unroll
;                     for (int bj = 0; bj < 2; ++bj)
; #pragma unroll
;                         for (int n = 0; n < 2; ++n) x[bj][n] = x[bj][n] * rinv * gn[bj][n];
;                 }
;                 if (rope && row < NLAT) {
;                     const int t = row & (T - 1), pr = t >> 6, pc = t & 63;
;                     const int idx = (fq < 2) ? (pr * 16 + 8 * fq) : (pc * 16 + 8 * fq - 16);
; #pragma unroll
;                     for (int n = 0; n < 2; ++n) {
;                         const f32x4 cs = *(const f32x4*)(ROPE_COS + idx + 4 * n), sn = *(const f32x4*)(ROPE_SIN + idx + 4 * n);
;                         const f32x4 x1 = x[0][n], x2 = x[1][n];
;                         x[0][n] = x1 * cs - x2 * sn;
;                         x[1][n] = x2 * cs + x1 * sn;
;                     }
;                 }
;                 bf16_t* rp = dst + (size_t)row * ld + dcol + 8 * fq;
; #pragma unroll
;                 for (int bj = 0; bj < 2; ++bj) {
;                     const f32x4 v0 = x[bj][0] * scale, v1 = x[bj][1] * scale;
;                     u32x4 w; w.x = pack2(v0[0], v0[1]); w.y = pack2(v0[2], v0[3]); w.z = pack2(v1[0], v1[1]); w.w = pack2(v1[2], v1[3]);
;                     *(u32x4*)(rp + 32 * bj) = w;
;                 }
.LBB0_377:
	s_or_b64 exec, exec, s[56:57]
	v_ashrrev_i32_e32 v132, 31, v131
	v_mul_lo_u32 v135, s52, v132
	v_mad_u64_u32 v[132:133], s[56:57], s52, v131, 0
	s_mov_b32 s51, s50
	v_mul_lo_u32 v134, s53, v131
	s_mov_b32 s56, s50
	s_mov_b32 s57, s50
	v_add3_u32 v133, v133, v135, v134
	v_pk_mul_f32 v[126:127], s[56:57], v[126:127]
	v_pk_mul_f32 v[124:125], s[50:51], v[124:125]
	v_pk_mul_f32 v[134:135], s[56:57], v[122:123]
	v_pk_mul_f32 v[122:123], s[50:51], v[120:121]
	v_lshl_add_u64 v[132:133], v[132:133], 1, v[156:157]
	v_cvt_pk_bf16_f32 v120, v124, v125
	v_cvt_pk_bf16_f32 v121, v126, v127
	v_cvt_pk_bf16_f32 v122, v122, v123
	v_cvt_pk_bf16_f32 v123, v134, v135
	global_store_dwordx4 v[132:133], v[120:123], off
	v_pk_mul_f32 v[118:119], s[56:57], v[118:119]
	v_pk_mul_f32 v[116:117], s[50:51], v[116:117]
	v_pk_mul_f32 v[120:121], s[56:57], v[114:115]
	v_pk_mul_f32 v[114:115], s[50:51], v[112:113]
	v_cvt_pk_bf16_f32 v112, v116, v117
	v_cvt_pk_bf16_f32 v113, v118, v119
	v_cvt_pk_bf16_f32 v114, v114, v115
	v_cvt_pk_bf16_f32 v115, v120, v121
	s_and_b64 vcc, exec, s[40:41]
	global_store_dwordx4 v[132:133], v[112:115], off offset:64
	s_cbranch_vccnz .LBB0_379
	v_mul_f32_e32 v116, v109, v109
	v_fmac_f32_e32 v116, v108, v108
	v_fmac_f32_e32 v116, v110, v110
	v_fmac_f32_e32 v116, v111, v111
	v_fmac_f32_e32 v116, v104, v104
	v_fmac_f32_e32 v116, v105, v105
	v_fmac_f32_e32 v116, v106, v106
	v_fmac_f32_e32 v116, v107, v107
	v_pk_mul_f32 v[114:115], v[100:101], v[100:101]
	v_pk_mul_f32 v[112:113], v[102:103], v[102:103]
	v_add_f32_e32 v114, v116, v114
	v_add_f32_e32 v114, v115, v114
	v_add_f32_e32 v112, v112, v114
	v_add_f32_e32 v116, v113, v112
	v_pk_mul_f32 v[114:115], v[96:97], v[96:97]
	v_pk_mul_f32 v[112:113], v[98:99], v[98:99]
	v_add_f32_e32 v114, v114, v116
	v_add_f32_e32 v114, v115, v114
	v_add_f32_e32 v112, v112, v114
	v_add_f32_e32 v112, v113, v112
	ds_bpermute_b32 v113, v164, v112
	s_waitcnt lgkmcnt(0)
	v_add_f32_e32 v112, v112, v113
	ds_bpermute_b32 v113, v165, v112
	s_waitcnt lgkmcnt(0)
	v_add_f32_e32 v112, v112, v113
	v_fmamk_f32 v112, v112, 0x3c800000, v170
	v_mul_f32_e32 v113, 0x4b800000, v112
	v_cmp_gt_f32_e32 vcc, s75, v112
	s_nop 1
	v_cndmask_b32_e32 v112, v112, v113, vcc
	v_rsq_f32_e32 v112, v112
	s_nop 0
	v_mul_f32_e32 v113, 0x45800000, v112
	v_cndmask_b32_e32 v112, v112, v113, vcc
	v_pk_mul_f32 v[108:109], v[108:109], v[112:113] op_sel_hi:[1,0]
	v_pk_mul_f32 v[110:111], v[110:111], v[112:113] op_sel_hi:[1,0]
	v_pk_mul_f32 v[104:105], v[104:105], v[112:113] op_sel_hi:[1,0]
	v_pk_mul_f32 v[106:107], v[106:107], v[112:113] op_sel_hi:[1,0]
	v_pk_mul_f32 v[100:101], v[100:101], v[112:113] op_sel_hi:[1,0]
	v_pk_mul_f32 v[102:103], v[102:103], v[112:113] op_sel_hi:[1,0]
	v_pk_mul_f32 v[96:97], v[96:97], v[112:113] op_sel_hi:[1,0]
	v_pk_mul_f32 v[98:99], v[98:99], v[112:113] op_sel_hi:[1,0]
	v_pk_mul_f32 v[110:111], v[70:71], v[110:111]
	v_pk_mul_f32 v[108:109], v[68:69], v[108:109]
	v_pk_mul_f32 v[106:107], v[66:67], v[106:107]
	v_pk_mul_f32 v[104:105], v[64:65], v[104:105]
	v_pk_mul_f32 v[102:103], v[82:83], v[102:103]
	v_pk_mul_f32 v[100:101], v[80:81], v[100:101]
	v_pk_mul_f32 v[98:99], v[74:75], v[98:99]
	v_pk_mul_f32 v[96:97], v[72:73], v[96:97]

; DI float shx(float v, int k, int lane) { return __builtin_bit_cast(float, __builtin_amdgcn_ds_bpermute((lane ^ k) << 2, __builtin_bit_cast(int, v))); }
; DI unsigned pack2(float lo, float hi) { f32x2 v = {lo, hi}; bf16x2_t b = __builtin_convertvector(v, bf16x2_t); return __builtin_bit_cast(unsigned, b); }
;     DI void operator()(const f32x4 (&acc)[2][2][4][2], const Unit& u, int wr, int wc, int fr_in, int fq_in) const {
;     ...
;                 if (gain) {
;                     float ss = 0.f;
; #pragma unroll
;                     for (int bj = 0; bj < 2; ++bj)
; #pragma unroll
;                         for (int n = 0; n < 2; ++n)
; #pragma unroll
;                             for (int e = 0; e < 4; ++e) ss += x[bj][n][e] * x[bj][n][e];
;                     ss += shx(ss, 16, fq * 16 + fr); ss += shx(ss, 32, fq * 16 + fr);
;                     const float rinv = rsqrtf(ss * (1.0f / 64.0f) + EPS);
; #pragma unroll
;                     for (int bj = 0; bj < 2; ++bj)
; #pragma unroll
;                         for (int n = 0; n < 2; ++n) x[bj][n] = x[bj][n] * rinv * gn[bj][n];
;                 }
;                 if (rope && row < NLAT) {
;                     const int t = row & (T - 1), pr = t >> 6, pc = t & 63;
;                     const int idx = (fq < 2) ? (pr * 16 + 8 * fq) : (pc * 16 + 8 * fq - 16);
; #pragma unroll
;                     for (int n = 0; n < 2; ++n) {
;                         const f32x4 cs = *(const f32x4*)(ROPE_COS + idx + 4 * n), sn = *(const f32x4*)(ROPE_SIN + idx + 4 * n);
;                         const f32x4 x1 = x[0][n], x2 = x[1][n];
;                         x[0][n] = x1 * cs - x2 * sn;
;                         x[1][n] = x2 * cs + x1 * sn;
;                     }
;                 }
;                 bf16_t* rp = dst + (size_t)row * ld + dcol + 8 * fq;
; #pragma unroll
;                 for (int bj = 0; bj < 2; ++bj) {
;                     const f32x4 v0 = x[bj][0] * scale, v1 = x[bj][1] * scale;
;                     u32x4 w; w.x = pack2(v0[0], v0[1]); w.y = pack2(v0[2], v0[3]); w.z = pack2(v1[0], v1[1]); w.w = pack2(v1[2], v1[3]);
;                     *(u32x4*)(rp + 32 * bj) = w;
;                 }
.LBB0_381:
	s_or_b64 exec, exec, s[56:57]
	v_ashrrev_i32_e32 v113, 31, v112
	v_mul_lo_u32 v114, s53, v112
	v_mul_lo_u32 v115, s52, v113
	v_mad_u64_u32 v[112:113], s[56:57], s52, v112, 0
	s_mov_b32 s56, s50
	s_mov_b32 s57, s50
	v_add3_u32 v113, v113, v115, v114
	v_pk_mul_f32 v[110:111], s[56:57], v[110:111]
	v_pk_mul_f32 v[108:109], s[50:51], v[108:109]
	v_pk_mul_f32 v[114:115], s[56:57], v[106:107]
	v_pk_mul_f32 v[106:107], s[50:51], v[104:105]
	v_lshl_add_u64 v[112:113], v[112:113], 1, v[156:157]
	v_cvt_pk_bf16_f32 v104, v108, v109
	v_cvt_pk_bf16_f32 v105, v110, v111
	v_cvt_pk_bf16_f32 v106, v106, v107
	v_cvt_pk_bf16_f32 v107, v114, v115
	global_store_dwordx4 v[112:113], v[104:107], off
	v_pk_mul_f32 v[102:103], s[56:57], v[102:103]
	v_pk_mul_f32 v[100:101], s[50:51], v[100:101]
	v_pk_mul_f32 v[104:105], s[56:57], v[98:99]
	v_pk_mul_f32 v[98:99], s[50:51], v[96:97]
	v_cvt_pk_bf16_f32 v96, v100, v101
	v_cvt_pk_bf16_f32 v97, v102, v103
	v_cvt_pk_bf16_f32 v98, v98, v99
	v_cvt_pk_bf16_f32 v99, v104, v105
	s_and_b64 vcc, exec, s[40:41]
	global_store_dwordx4 v[112:113], v[96:99], off offset:64
	s_cbranch_vccnz .LBB0_383
	v_mul_f32_e32 v100, v93, v93
	v_fmac_f32_e32 v100, v92, v92
	v_fmac_f32_e32 v100, v94, v94
	v_fmac_f32_e32 v100, v95, v95
	v_fmac_f32_e32 v100, v88, v88
	v_fmac_f32_e32 v100, v89, v89
	v_fmac_f32_e32 v100, v90, v90
	v_fmac_f32_e32 v100, v91, v91
	v_pk_mul_f32 v[98:99], v[84:85], v[84:85]
	v_pk_mul_f32 v[96:97], v[86:87], v[86:87]
	v_add_f32_e32 v98, v100, v98
	v_add_f32_e32 v98, v99, v98
	v_add_f32_e32 v96, v96, v98
	v_add_f32_e32 v100, v97, v96
	v_pk_mul_f32 v[98:99], v[76:77], v[76:77]
	v_pk_mul_f32 v[96:97], v[78:79], v[78:79]
	v_add_f32_e32 v98, v98, v100
	v_add_f32_e32 v98, v99, v98
	v_add_f32_e32 v96, v96, v98
	v_add_f32_e32 v96, v97, v96
	ds_bpermute_b32 v97, v164, v96
	s_waitcnt lgkmcnt(0)
	v_add_f32_e32 v96, v96, v97
	ds_bpermute_b32 v97, v165, v96
	s_waitcnt lgkmcnt(0)
	v_add_f32_e32 v96, v96, v97
	v_fmamk_f32 v96, v96, 0x3c800000, v170
	v_mul_f32_e32 v97, 0x4b800000, v96
	v_cmp_gt_f32_e32 vcc, s75, v96
	s_nop 1
	v_cndmask_b32_e32 v96, v96, v97, vcc
	v_rsq_f32_e32 v96, v96
	s_nop 0
	v_mul_f32_e32 v97, 0x45800000, v96
	v_cndmask_b32_e32 v96, v96, v97, vcc
	v_pk_mul_f32 v[92:93], v[92:93], v[96:97] op_sel_hi:[1,0]
	v_pk_mul_f32 v[94:95], v[94:95], v[96:97] op_sel_hi:[1,0]
	v_pk_mul_f32 v[88:89], v[88:89], v[96:97] op_sel_hi:[1,0]
	v_pk_mul_f32 v[90:91], v[90:91], v[96:97] op_sel_hi:[1,0]
	v_pk_mul_f32 v[84:85], v[84:85], v[96:97] op_sel_hi:[1,0]
	v_pk_mul_f32 v[86:87], v[86:87], v[96:97] op_sel_hi:[1,0]
	v_pk_mul_f32 v[76:77], v[76:77], v[96:97] op_sel_hi:[1,0]
	v_pk_mul_f32 v[78:79], v[78:79], v[96:97] op_sel_hi:[1,0]
	v_pk_mul_f32 v[94:95], v[70:71], v[94:95]
	v_pk_mul_f32 v[92:93], v[68:69], v[92:93]
	v_pk_mul_f32 v[90:91], v[66:67], v[90:91]
	v_pk_mul_f32 v[88:89], v[64:65], v[88:89]
	v_pk_mul_f32 v[86:87], v[82:83], v[86:87]
	v_pk_mul_f32 v[84:85], v[80:81], v[84:85]
	v_pk_mul_f32 v[78:79], v[74:75], v[78:79]
	v_pk_mul_f32 v[76:77], v[72:73], v[76:77]

; DI float shx(float v, int k, int lane) { return __builtin_bit_cast(float, __builtin_amdgcn_ds_bpermute((lane ^ k) << 2, __builtin_bit_cast(int, v))); }
; DI unsigned pack2(float lo, float hi) { f32x2 v = {lo, hi}; bf16x2_t b = __builtin_convertvector(v, bf16x2_t); return __builtin_bit_cast(unsigned, b); }
;     DI void operator()(const f32x4 (&acc)[2][2][4][2], const Unit& u, int wr, int wc, int fr_in, int fq_in) const {
;     ...
;                 if (gain) {
;                     float ss = 0.f;
; #pragma unroll
;                     for (int bj = 0; bj < 2; ++bj)
; #pragma unroll
;                         for (int n = 0; n < 2; ++n)
; #pragma unroll
;                             for (int e = 0; e < 4; ++e) ss += x[bj][n][e] * x[bj][n][e];
;                     ss += shx(ss, 16, fq * 16 + fr); ss += shx(ss, 32, fq * 16 + fr);
;                     const float rinv = rsqrtf(ss * (1.0f / 64.0f) + EPS);
; #pragma unroll
;                     for (int bj = 0; bj < 2; ++bj)
; #pragma unroll
;                         for (int n = 0; n < 2; ++n) x[bj][n] = x[bj][n] * rinv * gn[bj][n];
;                 }
;                 if (rope && row < NLAT) {
;                     const int t = row & (T - 1), pr = t >> 6, pc = t & 63;
;                     const int idx = (fq < 2) ? (pr * 16 + 8 * fq) : (pc * 16 + 8 * fq - 16);
; #pragma unroll
;                     for (int n = 0; n < 2; ++n) {
;                         const f32x4 cs = *(const f32x4*)(ROPE_COS + idx + 4 * n), sn = *(const f32x4*)(ROPE_SIN + idx + 4 * n);
;                         const f32x4 x1 = x[0][n], x2 = x[1][n];
;                         x[0][n] = x1 * cs - x2 * sn;
;                         x[1][n] = x2 * cs + x1 * sn;
;                     }
;                 }
;                 bf16_t* rp = dst + (size_t)row * ld + dcol + 8 * fq;
; #pragma unroll
;                 for (int bj = 0; bj < 2; ++bj) {
;                     const f32x4 v0 = x[bj][0] * scale, v1 = x[bj][1] * scale;
;                     u32x4 w; w.x = pack2(v0[0], v0[1]); w.y = pack2(v0[2], v0[3]); w.z = pack2(v1[0], v1[1]); w.w = pack2(v1[2], v1[3]);
;                     *(u32x4*)(rp + 32 * bj) = w;
;                 }
.LBB0_385:
	s_or_b64 exec, exec, s[56:57]
	v_ashrrev_i32_e32 v97, 31, v96
	v_mul_lo_u32 v98, s53, v96
	v_mul_lo_u32 v99, s52, v97
	v_mad_u64_u32 v[96:97], s[56:57], s52, v96, 0
	s_mov_b32 s56, s50
	s_mov_b32 s57, s50
	v_add3_u32 v97, v97, v99, v98
	v_pk_mul_f32 v[94:95], s[56:57], v[94:95]
	v_pk_mul_f32 v[92:93], s[50:51], v[92:93]
	v_pk_mul_f32 v[98:99], s[56:57], v[90:91]
	v_pk_mul_f32 v[90:91], s[50:51], v[88:89]
	v_lshl_add_u64 v[96:97], v[96:97], 1, v[156:157]
	v_cvt_pk_bf16_f32 v88, v92, v93
	v_cvt_pk_bf16_f32 v89, v94, v95
	v_cvt_pk_bf16_f32 v90, v90, v91
	v_cvt_pk_bf16_f32 v91, v98, v99
	global_store_dwordx4 v[96:97], v[88:91], off
	v_pk_mul_f32 v[86:87], s[56:57], v[86:87]
	v_pk_mul_f32 v[84:85], s[50:51], v[84:85]
	v_pk_mul_f32 v[88:89], s[56:57], v[78:79]
	v_pk_mul_f32 v[78:79], s[50:51], v[76:77]
	v_cvt_pk_bf16_f32 v76, v84, v85
	v_cvt_pk_bf16_f32 v77, v86, v87
	v_cvt_pk_bf16_f32 v78, v78, v79
	v_cvt_pk_bf16_f32 v79, v88, v89
	s_and_b64 vcc, exec, s[40:41]
	global_store_dwordx4 v[96:97], v[76:79], off offset:64
	s_cbranch_vccnz .LBB0_387
	v_mul_f32_e32 v84, v61, v61
	v_fmac_f32_e32 v84, v60, v60
	v_fmac_f32_e32 v84, v62, v62
	v_fmac_f32_e32 v84, v63, v63
	v_fmac_f32_e32 v84, v56, v56
	v_fmac_f32_e32 v84, v57, v57
	v_fmac_f32_e32 v84, v58, v58
	v_fmac_f32_e32 v84, v59, v59
	v_pk_mul_f32 v[78:79], v[52:53], v[52:53]
	v_pk_mul_f32 v[76:77], v[54:55], v[54:55]
	v_add_f32_e32 v78, v84, v78
	v_add_f32_e32 v78, v79, v78
	v_add_f32_e32 v76, v76, v78
	v_add_f32_e32 v84, v77, v76
	v_pk_mul_f32 v[78:79], v[48:49], v[48:49]
	v_pk_mul_f32 v[76:77], v[50:51], v[50:51]
	v_add_f32_e32 v78, v78, v84
	v_add_f32_e32 v78, v79, v78
	v_add_f32_e32 v76, v76, v78
	v_add_f32_e32 v76, v77, v76
	ds_bpermute_b32 v77, v164, v76
	s_waitcnt lgkmcnt(0)
	v_add_f32_e32 v76, v76, v77
	ds_bpermute_b32 v77, v165, v76
	s_waitcnt lgkmcnt(0)
	v_add_f32_e32 v76, v76, v77
	v_fmamk_f32 v76, v76, 0x3c800000, v170
	v_mul_f32_e32 v77, 0x4b800000, v76
	v_cmp_gt_f32_e32 vcc, s75, v76
	s_nop 1
	v_cndmask_b32_e32 v76, v76, v77, vcc
	v_rsq_f32_e32 v76, v76
	s_nop 0
	v_mul_f32_e32 v77, 0x45800000, v76
	v_cndmask_b32_e32 v76, v76, v77, vcc
	v_pk_mul_f32 v[60:61], v[60:61], v[76:77] op_sel_hi:[1,0]
	v_pk_mul_f32 v[62:63], v[62:63], v[76:77] op_sel_hi:[1,0]
	v_pk_mul_f32 v[56:57], v[56:57], v[76:77] op_sel_hi:[1,0]
	v_pk_mul_f32 v[58:59], v[58:59], v[76:77] op_sel_hi:[1,0]
	v_pk_mul_f32 v[52:53], v[52:53], v[76:77] op_sel_hi:[1,0]
	v_pk_mul_f32 v[54:55], v[54:55], v[76:77] op_sel_hi:[1,0]
	v_pk_mul_f32 v[48:49], v[48:49], v[76:77] op_sel_hi:[1,0]
	v_pk_mul_f32 v[50:51], v[50:51], v[76:77] op_sel_hi:[1,0]
	v_pk_mul_f32 v[62:63], v[70:71], v[62:63]
	v_pk_mul_f32 v[60:61], v[68:69], v[60:61]
	v_pk_mul_f32 v[58:59], v[66:67], v[58:59]
	v_pk_mul_f32 v[56:57], v[64:65], v[56:57]
	v_pk_mul_f32 v[54:55], v[82:83], v[54:55]
	v_pk_mul_f32 v[52:53], v[80:81], v[52:53]
	v_pk_mul_f32 v[50:51], v[74:75], v[50:51]
	v_pk_mul_f32 v[48:49], v[72:73], v[48:49]

; DI float shx(float v, int k, int lane) { return __builtin_bit_cast(float, __builtin_amdgcn_ds_bpermute((lane ^ k) << 2, __builtin_bit_cast(int, v))); }
; DI unsigned pack2(float lo, float hi) { f32x2 v = {lo, hi}; bf16x2_t b = __builtin_convertvector(v, bf16x2_t); return __builtin_bit_cast(unsigned, b); }
;     DI void operator()(const f32x4 (&acc)[2][2][4][2], const Unit& u, int wr, int wc, int fr_in, int fq_in) const {
;     ...
;                 if (gain) {
;                     float ss = 0.f;
; #pragma unroll
;                     for (int bj = 0; bj < 2; ++bj)
; #pragma unroll
;                         for (int n = 0; n < 2; ++n)
; #pragma unroll
;                             for (int e = 0; e < 4; ++e) ss += x[bj][n][e] * x[bj][n][e];
;                     ss += shx(ss, 16, fq * 16 + fr); ss += shx(ss, 32, fq * 16 + fr);
;                     const float rinv = rsqrtf(ss * (1.0f / 64.0f) + EPS);
; #pragma unroll
;                     for (int bj = 0; bj < 2; ++bj)
; #pragma unroll
;                         for (int n = 0; n < 2; ++n) x[bj][n] = x[bj][n] * rinv * gn[bj][n];
;                 }
;                 if (rope && row < NLAT) {
;                     const int t = row & (T - 1), pr = t >> 6, pc = t & 63;
;                     const int idx = (fq < 2) ? (pr * 16 + 8 * fq) : (pc * 16 + 8 * fq - 16);
; #pragma unroll
;                     for (int n = 0; n < 2; ++n) {
;                         const f32x4 cs = *(const f32x4*)(ROPE_COS + idx + 4 * n), sn = *(const f32x4*)(ROPE_SIN + idx + 4 * n);
;                         const f32x4 x1 = x[0][n], x2 = x[1][n];
;                         x[0][n] = x1 * cs - x2 * sn;
;                         x[1][n] = x2 * cs + x1 * sn;
;                     }
;                 }
;                 bf16_t* rp = dst + (size_t)row * ld + dcol + 8 * fq;
; #pragma unroll
;                 for (int bj = 0; bj < 2; ++bj) {
;                     const f32x4 v0 = x[bj][0] * scale, v1 = x[bj][1] * scale;
;                     u32x4 w; w.x = pack2(v0[0], v0[1]); w.y = pack2(v0[2], v0[3]); w.z = pack2(v1[0], v1[1]); w.w = pack2(v1[2], v1[3]);
;                     *(u32x4*)(rp + 32 * bj) = w;
;                 }
.LBB0_393:
	s_or_b64 exec, exec, s[56:57]
	v_ashrrev_i32_e32 v76, 31, v78
	v_mul_lo_u32 v84, s52, v76
	v_mad_u64_u32 v[76:77], s[44:45], s52, v78, 0
	v_mul_lo_u32 v79, s53, v78
	s_mov_b32 s44, s50
	s_mov_b32 s45, s50
	v_add3_u32 v77, v77, v84, v79
	v_pk_mul_f32 v[62:63], s[44:45], v[62:63]
	v_pk_mul_f32 v[60:61], s[50:51], v[60:61]
	v_pk_mul_f32 v[78:79], s[44:45], v[58:59]
	v_pk_mul_f32 v[58:59], s[50:51], v[56:57]
	v_lshl_add_u64 v[76:77], v[76:77], 1, v[156:157]
	v_cvt_pk_bf16_f32 v56, v60, v61
	v_cvt_pk_bf16_f32 v57, v62, v63
	v_cvt_pk_bf16_f32 v58, v58, v59
	v_cvt_pk_bf16_f32 v59, v78, v79
	global_store_dwordx4 v[76:77], v[56:59], off
	v_pk_mul_f32 v[54:55], s[44:45], v[54:55]
	v_pk_mul_f32 v[52:53], s[50:51], v[52:53]
	v_pk_mul_f32 v[56:57], s[44:45], v[50:51]
	v_pk_mul_f32 v[50:51], s[50:51], v[48:49]
	v_cvt_pk_bf16_f32 v48, v52, v53
	v_cvt_pk_bf16_f32 v49, v54, v55
	v_cvt_pk_bf16_f32 v50, v50, v51
	v_cvt_pk_bf16_f32 v51, v56, v57
	s_and_b64 vcc, exec, s[40:41]
	global_store_dwordx4 v[76:77], v[48:51], off offset:64
	s_cbranch_vccnz .LBB0_395
	v_mul_f32_e32 v52, v45, v45
	v_fmac_f32_e32 v52, v44, v44
	v_fmac_f32_e32 v52, v46, v46
	v_fmac_f32_e32 v52, v47, v47
	v_fmac_f32_e32 v52, v40, v40
	v_fmac_f32_e32 v52, v41, v41
	v_fmac_f32_e32 v52, v42, v42
	v_fmac_f32_e32 v52, v43, v43
	v_pk_mul_f32 v[50:51], v[36:37], v[36:37]
	v_pk_mul_f32 v[48:49], v[38:39], v[38:39]
	v_add_f32_e32 v50, v52, v50
	v_add_f32_e32 v50, v51, v50
	v_add_f32_e32 v48, v48, v50
	v_add_f32_e32 v52, v49, v48
	v_pk_mul_f32 v[50:51], v[32:33], v[32:33]
	v_pk_mul_f32 v[48:49], v[34:35], v[34:35]
	v_add_f32_e32 v50, v50, v52
	v_add_f32_e32 v50, v51, v50
	v_add_f32_e32 v48, v48, v50
	v_add_f32_e32 v48, v49, v48
	ds_bpermute_b32 v49, v164, v48
	s_waitcnt lgkmcnt(0)
	v_add_f32_e32 v48, v48, v49
	ds_bpermute_b32 v49, v165, v48
	s_waitcnt lgkmcnt(0)
	v_add_f32_e32 v48, v48, v49
	v_fmamk_f32 v48, v48, 0x3c800000, v170
	v_mul_f32_e32 v49, 0x4b800000, v48
	v_cmp_gt_f32_e32 vcc, s75, v48
	s_nop 1
	v_cndmask_b32_e32 v48, v48, v49, vcc
	v_rsq_f32_e32 v48, v48
	s_nop 0
	v_mul_f32_e32 v49, 0x45800000, v48
	v_cndmask_b32_e32 v48, v48, v49, vcc
	v_pk_mul_f32 v[44:45], v[44:45], v[48:49] op_sel_hi:[1,0]
	v_pk_mul_f32 v[46:47], v[46:47], v[48:49] op_sel_hi:[1,0]
	v_pk_mul_f32 v[40:41], v[40:41], v[48:49] op_sel_hi:[1,0]
	v_pk_mul_f32 v[42:43], v[42:43], v[48:49] op_sel_hi:[1,0]
	v_pk_mul_f32 v[36:37], v[36:37], v[48:49] op_sel_hi:[1,0]
	v_pk_mul_f32 v[38:39], v[38:39], v[48:49] op_sel_hi:[1,0]
	v_pk_mul_f32 v[32:33], v[32:33], v[48:49] op_sel_hi:[1,0]
	v_pk_mul_f32 v[34:35], v[34:35], v[48:49] op_sel_hi:[1,0]
	v_pk_mul_f32 v[46:47], v[70:71], v[46:47]
	v_pk_mul_f32 v[44:45], v[68:69], v[44:45]
	v_pk_mul_f32 v[42:43], v[66:67], v[42:43]
	v_pk_mul_f32 v[40:41], v[64:65], v[40:41]
	v_pk_mul_f32 v[38:39], v[82:83], v[38:39]
	v_pk_mul_f32 v[36:37], v[80:81], v[36:37]
	v_pk_mul_f32 v[34:35], v[74:75], v[34:35]
	v_pk_mul_f32 v[32:33], v[72:73], v[32:33]

; DI float shx(float v, int k, int lane) { return __builtin_bit_cast(float, __builtin_amdgcn_ds_bpermute((lane ^ k) << 2, __builtin_bit_cast(int, v))); }
; DI unsigned pack2(float lo, float hi) { f32x2 v = {lo, hi}; bf16x2_t b = __builtin_convertvector(v, bf16x2_t); return __builtin_bit_cast(unsigned, b); }
;     DI void operator()(const f32x4 (&acc)[2][2][4][2], const Unit& u, int wr, int wc, int fr_in, int fq_in) const {
;     ...
;                 if (gain) {
;                     float ss = 0.f;
; #pragma unroll
;                     for (int bj = 0; bj < 2; ++bj)
; #pragma unroll
;                         for (int n = 0; n < 2; ++n)
; #pragma unroll
;                             for (int e = 0; e < 4; ++e) ss += x[bj][n][e] * x[bj][n][e];
;                     ss += shx(ss, 16, fq * 16 + fr); ss += shx(ss, 32, fq * 16 + fr);
;                     const float rinv = rsqrtf(ss * (1.0f / 64.0f) + EPS);
; #pragma unroll
;                     for (int bj = 0; bj < 2; ++bj)
; #pragma unroll
;                         for (int n = 0; n < 2; ++n) x[bj][n] = x[bj][n] * rinv * gn[bj][n];
;                 }
;                 if (rope && row < NLAT) {
;                     const int t = row & (T - 1), pr = t >> 6, pc = t & 63;
;                     const int idx = (fq < 2) ? (pr * 16 + 8 * fq) : (pc * 16 + 8 * fq - 16);
; #pragma unroll
;                     for (int n = 0; n < 2; ++n) {
;                         const f32x4 cs = *(const f32x4*)(ROPE_COS + idx + 4 * n), sn = *(const f32x4*)(ROPE_SIN + idx + 4 * n);
;                         const f32x4 x1 = x[0][n], x2 = x[1][n];
;                         x[0][n] = x1 * cs - x2 * sn;
;                         x[1][n] = x2 * cs + x1 * sn;
;                     }
;                 }
;                 bf16_t* rp = dst + (size_t)row * ld + dcol + 8 * fq;
; #pragma unroll
;                 for (int bj = 0; bj < 2; ++bj) {
;                     const f32x4 v0 = x[bj][0] * scale, v1 = x[bj][1] * scale;
;                     u32x4 w; w.x = pack2(v0[0], v0[1]); w.y = pack2(v0[2], v0[3]); w.z = pack2(v1[0], v1[1]); w.w = pack2(v1[2], v1[3]);
;                     *(u32x4*)(rp + 32 * bj) = w;
.LBB0_397:
	s_or_b64 exec, exec, s[44:45]
	v_ashrrev_i32_e32 v49, 31, v48
	v_mul_lo_u32 v50, s53, v48
	v_mul_lo_u32 v51, s52, v49
	v_mad_u64_u32 v[48:49], s[44:45], s52, v48, 0
	s_mov_b32 s44, s50
	s_mov_b32 s45, s50
	v_add3_u32 v49, v49, v51, v50
	v_pk_mul_f32 v[46:47], s[44:45], v[46:47]
	v_pk_mul_f32 v[44:45], s[50:51], v[44:45]
	v_pk_mul_f32 v[50:51], s[44:45], v[42:43]
	v_pk_mul_f32 v[42:43], s[50:51], v[40:41]
	v_lshl_add_u64 v[48:49], v[48:49], 1, v[156:157]
	v_cvt_pk_bf16_f32 v40, v44, v45
	v_cvt_pk_bf16_f32 v41, v46, v47
	v_cvt_pk_bf16_f32 v42, v42, v43
	v_cvt_pk_bf16_f32 v43, v50, v51
	global_store_dwordx4 v[48:49], v[40:43], off
	v_pk_mul_f32 v[38:39], s[44:45], v[38:39]
	v_pk_mul_f32 v[36:37], s[50:51], v[36:37]
	v_pk_mul_f32 v[40:41], s[44:45], v[34:35]
	v_pk_mul_f32 v[34:35], s[50:51], v[32:33]
	v_cvt_pk_bf16_f32 v32, v36, v37
	v_cvt_pk_bf16_f32 v33, v38, v39
	v_cvt_pk_bf16_f32 v34, v34, v35
	v_cvt_pk_bf16_f32 v35, v40, v41
	s_and_b64 vcc, exec, s[40:41]
	global_store_dwordx4 v[48:49], v[32:35], off offset:64
	s_cbranch_vccnz .LBB0_399
	v_mul_f32_e32 v36, v29, v29
	v_fmac_f32_e32 v36, v28, v28
	v_fmac_f32_e32 v36, v30, v30
	v_fmac_f32_e32 v36, v31, v31
	v_fmac_f32_e32 v36, v24, v24
	v_fmac_f32_e32 v36, v25, v25
	v_fmac_f32_e32 v36, v26, v26
	v_fmac_f32_e32 v36, v27, v27
	v_pk_mul_f32 v[34:35], v[20:21], v[20:21]
	v_pk_mul_f32 v[32:33], v[22:23], v[22:23]
	v_add_f32_e32 v34, v36, v34
	v_add_f32_e32 v34, v35, v34
	v_add_f32_e32 v32, v32, v34
	v_add_f32_e32 v36, v33, v32
	v_pk_mul_f32 v[34:35], v[16:17], v[16:17]
	v_pk_mul_f32 v[32:33], v[18:19], v[18:19]
	v_add_f32_e32 v34, v34, v36
	v_add_f32_e32 v34, v35, v34
	v_add_f32_e32 v32, v32, v34
	v_add_f32_e32 v32, v33, v32
	ds_bpermute_b32 v33, v164, v32
	s_waitcnt lgkmcnt(0)
	v_add_f32_e32 v32, v32, v33
	ds_bpermute_b32 v33, v165, v32
	s_waitcnt lgkmcnt(0)
	v_add_f32_e32 v32, v32, v33
	v_fmamk_f32 v32, v32, 0x3c800000, v170
	v_mul_f32_e32 v33, 0x4b800000, v32
	v_cmp_gt_f32_e32 vcc, s75, v32
	s_nop 1
	v_cndmask_b32_e32 v32, v32, v33, vcc
	v_rsq_f32_e32 v32, v32
	s_nop 0
	v_mul_f32_e32 v33, 0x45800000, v32
	v_cndmask_b32_e32 v32, v32, v33, vcc
	v_pk_mul_f32 v[28:29], v[28:29], v[32:33] op_sel_hi:[1,0]
	v_pk_mul_f32 v[30:31], v[30:31], v[32:33] op_sel_hi:[1,0]
	v_pk_mul_f32 v[24:25], v[24:25], v[32:33] op_sel_hi:[1,0]
	v_pk_mul_f32 v[26:27], v[26:27], v[32:33] op_sel_hi:[1,0]
	v_pk_mul_f32 v[20:21], v[20:21], v[32:33] op_sel_hi:[1,0]
	v_pk_mul_f32 v[22:23], v[22:23], v[32:33] op_sel_hi:[1,0]
	v_pk_mul_f32 v[16:17], v[16:17], v[32:33] op_sel_hi:[1,0]
	v_pk_mul_f32 v[18:19], v[18:19], v[32:33] op_sel_hi:[1,0]
	v_pk_mul_f32 v[30:31], v[70:71], v[30:31]
	v_pk_mul_f32 v[28:29], v[68:69], v[28:29]
	v_pk_mul_f32 v[26:27], v[66:67], v[26:27]
	v_pk_mul_f32 v[24:25], v[64:65], v[24:25]
	v_pk_mul_f32 v[22:23], v[82:83], v[22:23]
	v_pk_mul_f32 v[20:21], v[80:81], v[20:21]
	v_pk_mul_f32 v[18:19], v[74:75], v[18:19]
	v_pk_mul_f32 v[16:17], v[72:73], v[16:17]

; DI float shx(float v, int k, int lane) { return __builtin_bit_cast(float, __builtin_amdgcn_ds_bpermute((lane ^ k) << 2, __builtin_bit_cast(int, v))); }
; DI unsigned pack2(float lo, float hi) { f32x2 v = {lo, hi}; bf16x2_t b = __builtin_convertvector(v, bf16x2_t); return __builtin_bit_cast(unsigned, b); }
;     DI void operator()(const f32x4 (&acc)[2][2][4][2], const Unit& u, int wr, int wc, int fr_in, int fq_in) const {
;     ...
;                 if (gain) {
;                     float ss = 0.f;
; #pragma unroll
;                     for (int bj = 0; bj < 2; ++bj)
; #pragma unroll
;                         for (int n = 0; n < 2; ++n)
; #pragma unroll
;                             for (int e = 0; e < 4; ++e) ss += x[bj][n][e] * x[bj][n][e];
;                     ss += shx(ss, 16, fq * 16 + fr); ss += shx(ss, 32, fq * 16 + fr);
;                     const float rinv = rsqrtf(ss * (1.0f / 64.0f) + EPS);
; #pragma unroll
;                     for (int bj = 0; bj < 2; ++bj)
; #pragma unroll
;                         for (int n = 0; n < 2; ++n) x[bj][n] = x[bj][n] * rinv * gn[bj][n];
;                 }
;                 if (rope && row < NLAT) {
;                     const int t = row & (T - 1), pr = t >> 6, pc = t & 63;
;                     const int idx = (fq < 2) ? (pr * 16 + 8 * fq) : (pc * 16 + 8 * fq - 16);
; #pragma unroll
;                     for (int n = 0; n < 2; ++n) {
;                         const f32x4 cs = *(const f32x4*)(ROPE_COS + idx + 4 * n), sn = *(const f32x4*)(ROPE_SIN + idx + 4 * n);
;                         const f32x4 x1 = x[0][n], x2 = x[1][n];
;                         x[0][n] = x1 * cs - x2 * sn;
;                         x[1][n] = x2 * cs + x1 * sn;
;                     }
;                 }
;                 bf16_t* rp = dst + (size_t)row * ld + dcol + 8 * fq;
; #pragma unroll
;                 for (int bj = 0; bj < 2; ++bj) {
;                     const f32x4 v0 = x[bj][0] * scale, v1 = x[bj][1] * scale;
;                     u32x4 w; w.x = pack2(v0[0], v0[1]); w.y = pack2(v0[2], v0[3]); w.z = pack2(v1[0], v1[1]); w.w = pack2(v1[2], v1[3]);
;                     *(u32x4*)(rp + 32 * bj) = w;
.LBB0_401:
	s_or_b64 exec, exec, s[44:45]
	v_ashrrev_i32_e32 v33, 31, v32
	v_mul_lo_u32 v34, s53, v32
	v_mul_lo_u32 v35, s52, v33
	v_mad_u64_u32 v[32:33], s[44:45], s52, v32, 0
	s_mov_b32 s44, s50
	s_mov_b32 s45, s50
	v_add3_u32 v33, v33, v35, v34
	v_pk_mul_f32 v[30:31], s[44:45], v[30:31]
	v_pk_mul_f32 v[28:29], s[50:51], v[28:29]
	v_pk_mul_f32 v[34:35], s[44:45], v[26:27]
	v_pk_mul_f32 v[26:27], s[50:51], v[24:25]
	v_lshl_add_u64 v[32:33], v[32:33], 1, v[156:157]
	v_cvt_pk_bf16_f32 v24, v28, v29
	v_cvt_pk_bf16_f32 v25, v30, v31
	v_cvt_pk_bf16_f32 v26, v26, v27
	v_cvt_pk_bf16_f32 v27, v34, v35
	global_store_dwordx4 v[32:33], v[24:27], off
	v_pk_mul_f32 v[22:23], s[44:45], v[22:23]
	v_pk_mul_f32 v[20:21], s[50:51], v[20:21]
	v_pk_mul_f32 v[24:25], s[44:45], v[18:19]
	v_pk_mul_f32 v[18:19], s[50:51], v[16:17]
	v_cvt_pk_bf16_f32 v16, v20, v21
	v_cvt_pk_bf16_f32 v17, v22, v23
	v_cvt_pk_bf16_f32 v18, v18, v19
	v_cvt_pk_bf16_f32 v19, v24, v25
	s_and_b64 vcc, exec, s[40:41]
	global_store_dwordx4 v[32:33], v[16:19], off offset:64
	s_cbranch_vccnz .LBB0_403
	v_mul_f32_e32 v20, v13, v13
	v_fmac_f32_e32 v20, v12, v12
	v_fmac_f32_e32 v20, v14, v14
	v_fmac_f32_e32 v20, v15, v15
	v_fmac_f32_e32 v20, v8, v8
	v_fmac_f32_e32 v20, v9, v9
	v_fmac_f32_e32 v20, v10, v10
	v_fmac_f32_e32 v20, v11, v11
	v_pk_mul_f32 v[18:19], v[4:5], v[4:5]
	v_pk_mul_f32 v[16:17], v[6:7], v[6:7]
	v_add_f32_e32 v18, v20, v18
	v_add_f32_e32 v18, v19, v18
	v_add_f32_e32 v16, v16, v18
	v_add_f32_e32 v20, v17, v16
	v_pk_mul_f32 v[18:19], v[0:1], v[0:1]
	v_pk_mul_f32 v[16:17], v[2:3], v[2:3]
	v_add_f32_e32 v18, v18, v20
	v_add_f32_e32 v18, v19, v18
	v_add_f32_e32 v16, v16, v18
	v_add_f32_e32 v16, v17, v16
	ds_bpermute_b32 v17, v164, v16
	s_waitcnt lgkmcnt(0)
	v_add_f32_e32 v16, v16, v17
	ds_bpermute_b32 v17, v165, v16
	s_waitcnt lgkmcnt(0)
	v_add_f32_e32 v16, v16, v17
	v_fmamk_f32 v16, v16, 0x3c800000, v170
	v_mul_f32_e32 v17, 0x4b800000, v16
	v_cmp_gt_f32_e32 vcc, s75, v16
	s_nop 1
	v_cndmask_b32_e32 v16, v16, v17, vcc
	v_rsq_f32_e32 v16, v16
	s_nop 0
	v_mul_f32_e32 v17, 0x45800000, v16
	v_cndmask_b32_e32 v16, v16, v17, vcc
	v_pk_mul_f32 v[12:13], v[12:13], v[16:17] op_sel_hi:[1,0]
	v_pk_mul_f32 v[14:15], v[14:15], v[16:17] op_sel_hi:[1,0]
	v_pk_mul_f32 v[8:9], v[8:9], v[16:17] op_sel_hi:[1,0]
	v_pk_mul_f32 v[10:11], v[10:11], v[16:17] op_sel_hi:[1,0]
	v_pk_mul_f32 v[4:5], v[4:5], v[16:17] op_sel_hi:[1,0]
	v_pk_mul_f32 v[6:7], v[6:7], v[16:17] op_sel_hi:[1,0]
	v_pk_mul_f32 v[0:1], v[0:1], v[16:17] op_sel_hi:[1,0]
	v_pk_mul_f32 v[2:3], v[2:3], v[16:17] op_sel_hi:[1,0]
	v_pk_mul_f32 v[14:15], v[70:71], v[14:15]
	v_pk_mul_f32 v[12:13], v[68:69], v[12:13]
	v_pk_mul_f32 v[10:11], v[66:67], v[10:11]
	v_pk_mul_f32 v[8:9], v[64:65], v[8:9]
	v_pk_mul_f32 v[6:7], v[82:83], v[6:7]
	v_pk_mul_f32 v[4:5], v[80:81], v[4:5]
	v_pk_mul_f32 v[2:3], v[74:75], v[2:3]
	v_pk_mul_f32 v[0:1], v[72:73], v[0:1]
